# attention: early tail + softmax tail inside second QK chain + next sub-tile fragment prefetch (defer8)
# speedup vs baseline: 1.0115x; 1.0011x over previous
.Lnd_107:
	s_and_b32 s33, s42, 1
	s_mul_i32 s6, s33, 0x9000
	v_add_u32_e32 v199, s6, v187
	v_add_u32_e32 v198, s6, v188
	s_mov_b64 s[54:55], exec
	v_readfirstlane_b32 s4, v186
	s_bitcmp1_b32 s4, 8
	s_cbranch_scc1 .Lab_B
	ds_read_b128 v[216:219], v199 offset:0
	ds_read_b128 v[232:235], v193 offset:0
	ds_read_b128 v[220:223], v199 offset:32
	ds_read_b128 v[236:239], v193 offset:32
	ds_read_b128 v[224:227], v199 offset:64
	ds_read_b128 v[244:247], v193 offset:64
	ds_read_b128 v[228:231], v199 offset:96
	ds_read_b128 v[248:251], v193 offset:96
	s_waitcnt lgkmcnt(6)
	v_mfma_f32_32x32x16_bf16 v[144:159], v[216:219], v[232:235], v[0:15]
	s_waitcnt lgkmcnt(4)
	v_mfma_f32_32x32x16_bf16 v[144:159], v[220:223], v[236:239], v[144:159]
	s_waitcnt lgkmcnt(2)
	v_mfma_f32_32x32x16_bf16 v[144:159], v[224:227], v[244:247], v[144:159]
	s_waitcnt lgkmcnt(0)
	v_mfma_f32_32x32x16_bf16 v[144:159], v[228:231], v[248:251], v[144:159]
	ds_read_b128 v[216:219], v199 offset:9216
	ds_read_b128 v[232:235], v193 offset:36864
	ds_read_b128 v[220:223], v199 offset:9248
	ds_read_b128 v[236:239], v193 offset:36896
	ds_read_b128 v[224:227], v199 offset:9280
	ds_read_b128 v[244:247], v193 offset:36928
	ds_read_b128 v[228:231], v199 offset:9312
	ds_read_b128 v[248:251], v193 offset:36960
	s_nop 3
	v_exp_f32_e32 v144, v144
	v_exp_f32_e32 v145, v145
	v_exp_f32_e32 v146, v146
	v_exp_f32_e32 v147, v147
	v_exp_f32_e32 v148, v148
	v_exp_f32_e32 v149, v149
	v_exp_f32_e32 v150, v150
	v_exp_f32_e32 v151, v151
	v_exp_f32_e32 v152, v152
	v_exp_f32_e32 v153, v153
	v_exp_f32_e32 v154, v154
	v_exp_f32_e32 v155, v155
	v_exp_f32_e32 v156, v156
	v_exp_f32_e32 v157, v157
	v_exp_f32_e32 v158, v158
	v_exp_f32_e32 v159, v159
	v_add_f32_e32 v243, v144, v145
	v_add_f32_e32 v243, v146, v243
	v_add_f32_e32 v243, v147, v243
	v_add_f32_e32 v243, v148, v243
	v_add_f32_e32 v243, v149, v243
	v_add_f32_e32 v243, v150, v243
	v_add_f32_e32 v243, v151, v243
	s_waitcnt lgkmcnt(6)
	v_mfma_f32_32x32x16_bf16 v[200:215], v[216:219], v[232:235], v[0:15]
	v_add_f32_e32 v243, v152, v243
	v_add_f32_e32 v243, v153, v243
	v_add_f32_e32 v243, v154, v243
	v_add_f32_e32 v243, v155, v243
	s_waitcnt lgkmcnt(4)
	v_mfma_f32_32x32x16_bf16 v[200:215], v[220:223], v[236:239], v[200:215]
	v_add_f32_e32 v243, v156, v243
	v_add_f32_e32 v243, v157, v243
	v_add_f32_e32 v243, v158, v243
	v_add_f32_e32 v243, v159, v243
	s_waitcnt lgkmcnt(2)
	v_mfma_f32_32x32x16_bf16 v[200:215], v[224:227], v[244:247], v[200:215]
	v_add_f32_e32 v196, v196, v243
	v_cvt_pk_bf16_f32 v144, v144, v145
	v_cvt_pk_bf16_f32 v145, v146, v147
	v_cvt_pk_bf16_f32 v146, v148, v149
	s_waitcnt lgkmcnt(0)
	v_mfma_f32_32x32x16_bf16 v[200:215], v[228:231], v[248:251], v[200:215]
	ds_read_b128 v[216:219], v198 offset:0
	ds_read_b128 v[224:227], v198 offset:4608
	ds_read_b128 v[232:235], v198 offset:9216
	ds_read_b128 v[244:247], v198 offset:13824
	ds_read_b128 v[220:223], v198 offset:32
	ds_read_b128 v[228:231], v198 offset:4640
	ds_read_b128 v[236:239], v198 offset:9248
	ds_read_b128 v[248:251], v198 offset:13856
	v_cvt_pk_bf16_f32 v147, v150, v151
	v_cvt_pk_bf16_f32 v148, v152, v153
	v_cvt_pk_bf16_f32 v149, v154, v155
	v_cvt_pk_bf16_f32 v150, v156, v157
	v_cvt_pk_bf16_f32 v151, v158, v159
	s_waitcnt lgkmcnt(7)
	v_mfma_f32_32x32x16_bf16 v[112:127], v[216:219], v[144:147], v[112:127]
	v_exp_f32_e32 v200, v200
	v_exp_f32_e32 v201, v201
	v_exp_f32_e32 v202, v202
	v_exp_f32_e32 v203, v203
	v_exp_f32_e32 v204, v204
	s_waitcnt lgkmcnt(6)
	v_mfma_f32_32x32x16_bf16 v[80:95], v[224:227], v[144:147], v[80:95]
	v_exp_f32_e32 v205, v205
	v_exp_f32_e32 v206, v206
	v_exp_f32_e32 v207, v207
	v_exp_f32_e32 v208, v208
	v_exp_f32_e32 v209, v209
	s_waitcnt lgkmcnt(5)
	v_mfma_f32_32x32x16_bf16 v[48:63], v[232:235], v[144:147], v[48:63]
	v_exp_f32_e32 v210, v210
	v_exp_f32_e32 v211, v211
	v_exp_f32_e32 v212, v212
	v_exp_f32_e32 v213, v213
	v_exp_f32_e32 v214, v214
	s_waitcnt lgkmcnt(4)
	v_mfma_f32_32x32x16_bf16 v[16:31], v[244:247], v[144:147], v[16:31]
	v_exp_f32_e32 v215, v215
	v_add_f32_e32 v243, v200, v201
	v_add_f32_e32 v243, v202, v243
	v_add_f32_e32 v243, v203, v243
	v_add_f32_e32 v243, v204, v243
	s_waitcnt lgkmcnt(3)
	v_mfma_f32_32x32x16_bf16 v[112:127], v[220:223], v[148:151], v[112:127]
	v_add_f32_e32 v243, v205, v243
	v_add_f32_e32 v243, v206, v243
	v_add_f32_e32 v243, v207, v243
	v_add_f32_e32 v243, v208, v243
	v_add_f32_e32 v243, v209, v243
	s_waitcnt lgkmcnt(2)
	v_mfma_f32_32x32x16_bf16 v[80:95], v[228:231], v[148:151], v[80:95]
	v_add_f32_e32 v243, v210, v243
	v_add_f32_e32 v243, v211, v243
	v_add_f32_e32 v243, v212, v243
	v_add_f32_e32 v243, v213, v243
	v_add_f32_e32 v243, v214, v243
	s_waitcnt lgkmcnt(1)
	v_mfma_f32_32x32x16_bf16 v[48:63], v[236:239], v[148:151], v[48:63]
	v_add_f32_e32 v243, v215, v243
	v_add_f32_e32 v197, v197, v243
	v_cvt_pk_bf16_f32 v200, v200, v201
	v_cvt_pk_bf16_f32 v201, v202, v203
	v_cvt_pk_bf16_f32 v202, v204, v205
	s_waitcnt lgkmcnt(0)
	v_mfma_f32_32x32x16_bf16 v[16:31], v[248:251], v[148:151], v[16:31]
	v_cvt_pk_bf16_f32 v203, v206, v207
	v_cvt_pk_bf16_f32 v204, v208, v209
	v_cvt_pk_bf16_f32 v205, v210, v211
	v_cvt_pk_bf16_f32 v206, v212, v213
	v_cvt_pk_bf16_f32 v207, v214, v215
	ds_read_b128 v[252:255], v199 offset:4608
	ds_read_b128 v[208:211], v193
	ds_read_b128 v[212:215], v199 offset:4640
	v_mfma_f32_32x32x16_bf16 v[128:143], v[216:219], v[200:203], v[128:143]
	v_mfma_f32_32x32x16_bf16 v[96:111], v[224:227], v[200:203], v[96:111]
	v_mfma_f32_32x32x16_bf16 v[64:79], v[232:235], v[200:203], v[64:79]
	v_mfma_f32_32x32x16_bf16 v[32:47], v[244:247], v[200:203], v[32:47]
	v_mfma_f32_32x32x16_bf16 v[128:143], v[220:223], v[204:207], v[128:143]
	v_mfma_f32_32x32x16_bf16 v[96:111], v[228:231], v[204:207], v[96:111]
	v_mfma_f32_32x32x16_bf16 v[64:79], v[236:239], v[204:207], v[64:79]
	v_mfma_f32_32x32x16_bf16 v[32:47], v[248:251], v[204:207], v[32:47]
	ds_read_b128 v[236:239], v193 offset:32
	ds_read_b128 v[224:227], v199 offset:4672
	ds_read_b128 v[244:247], v193 offset:64
	ds_read_b128 v[228:231], v199 offset:4704
	ds_read_b128 v[248:251], v193 offset:96
	s_waitcnt lgkmcnt(6)
	v_mfma_f32_32x32x16_bf16 v[144:159], v[252:255], v[208:211], v[0:15]
	s_waitcnt lgkmcnt(4)
	v_mfma_f32_32x32x16_bf16 v[144:159], v[212:215], v[236:239], v[144:159]
	s_waitcnt lgkmcnt(2)
	v_mfma_f32_32x32x16_bf16 v[144:159], v[224:227], v[244:247], v[144:159]
	s_waitcnt lgkmcnt(0)
	v_mfma_f32_32x32x16_bf16 v[144:159], v[228:231], v[248:251], v[144:159]
	ds_read_b128 v[216:219], v199 offset:13824
	ds_read_b128 v[232:235], v193 offset:36864
	ds_read_b128 v[220:223], v199 offset:13856
	ds_read_b128 v[236:239], v193 offset:36896
	ds_read_b128 v[224:227], v199 offset:13888
	ds_read_b128 v[244:247], v193 offset:36928
	ds_read_b128 v[228:231], v199 offset:13920
	ds_read_b128 v[248:251], v193 offset:36960
	s_nop 3
	v_exp_f32_e32 v144, v144
	v_exp_f32_e32 v145, v145
	v_exp_f32_e32 v146, v146
	v_exp_f32_e32 v147, v147
	v_exp_f32_e32 v148, v148
	v_exp_f32_e32 v149, v149
	v_exp_f32_e32 v150, v150
	v_exp_f32_e32 v151, v151
	v_exp_f32_e32 v152, v152
	v_exp_f32_e32 v153, v153
	v_exp_f32_e32 v154, v154
	v_exp_f32_e32 v155, v155
	v_exp_f32_e32 v156, v156
	v_exp_f32_e32 v157, v157
	v_exp_f32_e32 v158, v158
	v_exp_f32_e32 v159, v159
	v_add_f32_e32 v243, v144, v145
	v_add_f32_e32 v243, v146, v243
	v_add_f32_e32 v243, v147, v243
	v_add_f32_e32 v243, v148, v243
	v_add_f32_e32 v243, v149, v243
	v_add_f32_e32 v243, v150, v243
	v_add_f32_e32 v243, v151, v243
	s_waitcnt lgkmcnt(6)
	v_mfma_f32_32x32x16_bf16 v[200:215], v[216:219], v[232:235], v[0:15]
	v_add_f32_e32 v243, v152, v243
	v_add_f32_e32 v243, v153, v243
	v_add_f32_e32 v243, v154, v243
	v_add_f32_e32 v243, v155, v243
	s_waitcnt lgkmcnt(4)
	v_mfma_f32_32x32x16_bf16 v[200:215], v[220:223], v[236:239], v[200:215]
	v_add_f32_e32 v243, v156, v243
	v_add_f32_e32 v243, v157, v243
	v_add_f32_e32 v243, v158, v243
	v_add_f32_e32 v243, v159, v243
	s_waitcnt lgkmcnt(2)
	v_mfma_f32_32x32x16_bf16 v[200:215], v[224:227], v[244:247], v[200:215]
	v_add_f32_e32 v196, v196, v243
	v_cvt_pk_bf16_f32 v144, v144, v145
	v_cvt_pk_bf16_f32 v145, v146, v147
	v_cvt_pk_bf16_f32 v146, v148, v149
	s_waitcnt lgkmcnt(0)
	v_mfma_f32_32x32x16_bf16 v[200:215], v[228:231], v[248:251], v[200:215]
	ds_read_b128 v[216:219], v198 offset:64
	ds_read_b128 v[224:227], v198 offset:4672
	ds_read_b128 v[232:235], v198 offset:9280
	ds_read_b128 v[244:247], v198 offset:13888
	ds_read_b128 v[220:223], v198 offset:96
	ds_read_b128 v[228:231], v198 offset:4704
	ds_read_b128 v[236:239], v198 offset:9312
	ds_read_b128 v[248:251], v198 offset:13920
	v_cvt_pk_bf16_f32 v147, v150, v151
	v_cvt_pk_bf16_f32 v148, v152, v153
	v_cvt_pk_bf16_f32 v149, v154, v155
	v_cvt_pk_bf16_f32 v150, v156, v157
	v_cvt_pk_bf16_f32 v151, v158, v159
	s_waitcnt lgkmcnt(7)
	v_mfma_f32_32x32x16_bf16 v[112:127], v[216:219], v[144:147], v[112:127]
	v_exp_f32_e32 v200, v200
	v_exp_f32_e32 v201, v201
	v_exp_f32_e32 v202, v202
	v_exp_f32_e32 v203, v203
	v_exp_f32_e32 v204, v204
	s_waitcnt lgkmcnt(6)
	v_mfma_f32_32x32x16_bf16 v[80:95], v[224:227], v[144:147], v[80:95]
	v_exp_f32_e32 v205, v205
	v_exp_f32_e32 v206, v206
	v_exp_f32_e32 v207, v207
	v_exp_f32_e32 v208, v208
	v_exp_f32_e32 v209, v209
	s_waitcnt lgkmcnt(5)
	v_mfma_f32_32x32x16_bf16 v[48:63], v[232:235], v[144:147], v[48:63]
	v_exp_f32_e32 v210, v210
	v_exp_f32_e32 v211, v211
	v_exp_f32_e32 v212, v212
	v_exp_f32_e32 v213, v213
	v_exp_f32_e32 v214, v214
	s_waitcnt lgkmcnt(4)
	v_mfma_f32_32x32x16_bf16 v[16:31], v[244:247], v[144:147], v[16:31]
	v_exp_f32_e32 v215, v215
	v_add_f32_e32 v243, v200, v201
	v_add_f32_e32 v243, v202, v243
	v_add_f32_e32 v243, v203, v243
	v_add_f32_e32 v243, v204, v243
	s_waitcnt lgkmcnt(3)
	v_mfma_f32_32x32x16_bf16 v[112:127], v[220:223], v[148:151], v[112:127]
	v_add_f32_e32 v243, v205, v243
	v_add_f32_e32 v243, v206, v243
	v_add_f32_e32 v243, v207, v243
	v_add_f32_e32 v243, v208, v243
	v_add_f32_e32 v243, v209, v243
	s_waitcnt lgkmcnt(2)
	v_mfma_f32_32x32x16_bf16 v[80:95], v[228:231], v[148:151], v[80:95]
	v_add_f32_e32 v243, v210, v243
	v_add_f32_e32 v243, v211, v243
	v_add_f32_e32 v243, v212, v243
	v_add_f32_e32 v243, v213, v243
	v_add_f32_e32 v243, v214, v243
	s_waitcnt lgkmcnt(1)
	v_mfma_f32_32x32x16_bf16 v[48:63], v[236:239], v[148:151], v[48:63]
	v_add_f32_e32 v243, v215, v243
	v_add_f32_e32 v197, v197, v243
	v_cvt_pk_bf16_f32 v200, v200, v201
	v_cvt_pk_bf16_f32 v201, v202, v203
	v_cvt_pk_bf16_f32 v202, v204, v205
	s_waitcnt lgkmcnt(0)
	v_mfma_f32_32x32x16_bf16 v[16:31], v[248:251], v[148:151], v[16:31]
	v_cvt_pk_bf16_f32 v203, v206, v207
	v_cvt_pk_bf16_f32 v204, v208, v209
	v_cvt_pk_bf16_f32 v205, v210, v211
	v_cvt_pk_bf16_f32 v206, v212, v213
	v_cvt_pk_bf16_f32 v207, v214, v215
	s_add_i32 s6, s42, 1
	s_waitcnt vmcnt(0)
	s_cmp_eq_u32 s33, 0
	s_cbranch_scc0 .Lqt_s0_1
	v_add_u32_e32 v252, 0x9000, v190
	ds_write_b128 v189, v[160:163] offset:36864
	ds_write2_b64 v252, v[164:165], v[166:167] offset1:2
	ds_write_b128 v189, v[168:171] offset:46080
	v_add_u32_e32 v252, 0xb000, v190
	ds_write2_b64 v252, v[172:173], v[174:175] offset0:128 offset1:130
	s_branch .Lqt_pf_1

.Lab_B0:
	ds_read_b128 v[216:219], v199 offset:0
	ds_read_b128 v[232:235], v193 offset:0
	ds_read_b128 v[220:223], v199 offset:32
	ds_read_b128 v[236:239], v193 offset:32
	ds_read_b128 v[224:227], v199 offset:64
	ds_read_b128 v[244:247], v193 offset:64
	ds_read_b128 v[228:231], v199 offset:96
	ds_read_b128 v[248:251], v193 offset:96
	s_waitcnt lgkmcnt(6)
	v_mfma_f32_32x32x16_bf16 v[144:159], v[216:219], v[232:235], v[0:15]
	s_waitcnt lgkmcnt(4)
	v_mfma_f32_32x32x16_bf16 v[144:159], v[220:223], v[236:239], v[144:159]
	s_waitcnt lgkmcnt(2)
	v_mfma_f32_32x32x16_bf16 v[144:159], v[224:227], v[244:247], v[144:159]
	s_waitcnt lgkmcnt(0)
	v_mfma_f32_32x32x16_bf16 v[144:159], v[228:231], v[248:251], v[144:159]
	ds_read_b128 v[216:219], v199 offset:9216
	ds_read_b128 v[232:235], v193 offset:36864
	ds_read_b128 v[220:223], v199 offset:9248
	ds_read_b128 v[236:239], v193 offset:36896
	ds_read_b128 v[224:227], v199 offset:9280
	ds_read_b128 v[244:247], v193 offset:36928
	ds_read_b128 v[228:231], v199 offset:9312
	ds_read_b128 v[248:251], v193 offset:36960
	s_nop 3
	v_exp_f32_e32 v144, v144
	v_exp_f32_e32 v145, v145
	v_exp_f32_e32 v146, v146
	v_exp_f32_e32 v147, v147
	v_exp_f32_e32 v148, v148
	v_exp_f32_e32 v149, v149
	v_exp_f32_e32 v150, v150
	v_exp_f32_e32 v151, v151
	v_exp_f32_e32 v152, v152
	v_exp_f32_e32 v153, v153
	v_exp_f32_e32 v154, v154
	v_exp_f32_e32 v155, v155
	v_exp_f32_e32 v156, v156
	v_exp_f32_e32 v157, v157
	v_exp_f32_e32 v158, v158
	v_exp_f32_e32 v159, v159
	v_add_f32_e32 v243, v144, v145
	v_add_f32_e32 v243, v146, v243
	v_add_f32_e32 v243, v147, v243
	v_add_f32_e32 v243, v148, v243
	v_add_f32_e32 v243, v149, v243
	v_add_f32_e32 v243, v150, v243
	v_add_f32_e32 v243, v151, v243
	s_waitcnt lgkmcnt(6)
	v_mfma_f32_32x32x16_bf16 v[200:215], v[216:219], v[232:235], v[0:15]
	v_add_f32_e32 v243, v152, v243
	v_add_f32_e32 v243, v153, v243
	v_add_f32_e32 v243, v154, v243
	v_add_f32_e32 v243, v155, v243
	s_waitcnt lgkmcnt(4)
	v_mfma_f32_32x32x16_bf16 v[200:215], v[220:223], v[236:239], v[200:215]
	v_add_f32_e32 v243, v156, v243
	v_add_f32_e32 v243, v157, v243
	v_add_f32_e32 v243, v158, v243
	v_add_f32_e32 v243, v159, v243
	s_waitcnt lgkmcnt(2)
	v_mfma_f32_32x32x16_bf16 v[200:215], v[224:227], v[244:247], v[200:215]
	v_add_f32_e32 v196, v196, v243
	v_cvt_pk_bf16_f32 v144, v144, v145
	v_cvt_pk_bf16_f32 v145, v146, v147
	v_cvt_pk_bf16_f32 v146, v148, v149
	s_waitcnt lgkmcnt(0)
	v_mfma_f32_32x32x16_bf16 v[200:215], v[228:231], v[248:251], v[200:215]
	ds_read_b128 v[216:219], v198 offset:0
	ds_read_b128 v[224:227], v198 offset:4608
	ds_read_b128 v[232:235], v198 offset:9216
	ds_read_b128 v[244:247], v198 offset:13824
	ds_read_b128 v[220:223], v198 offset:32
	ds_read_b128 v[228:231], v198 offset:4640
	ds_read_b128 v[236:239], v198 offset:9248
	ds_read_b128 v[248:251], v198 offset:13856
	v_cvt_pk_bf16_f32 v147, v150, v151
	v_cvt_pk_bf16_f32 v148, v152, v153
	v_cvt_pk_bf16_f32 v149, v154, v155
	v_cvt_pk_bf16_f32 v150, v156, v157
	v_cvt_pk_bf16_f32 v151, v158, v159
	s_waitcnt lgkmcnt(7)
	v_mfma_f32_32x32x16_bf16 v[112:127], v[216:219], v[144:147], v[112:127]
	v_exp_f32_e32 v200, v200
	v_exp_f32_e32 v201, v201
	v_exp_f32_e32 v202, v202
	v_exp_f32_e32 v203, v203
	v_exp_f32_e32 v204, v204
	s_waitcnt lgkmcnt(6)
	v_mfma_f32_32x32x16_bf16 v[80:95], v[224:227], v[144:147], v[80:95]
	v_exp_f32_e32 v205, v205
	v_exp_f32_e32 v206, v206
	v_exp_f32_e32 v207, v207
	v_exp_f32_e32 v208, v208
	v_exp_f32_e32 v209, v209
	s_waitcnt lgkmcnt(5)
	v_mfma_f32_32x32x16_bf16 v[48:63], v[232:235], v[144:147], v[48:63]
	v_exp_f32_e32 v210, v210
	v_exp_f32_e32 v211, v211
	v_exp_f32_e32 v212, v212
	v_exp_f32_e32 v213, v213
	v_exp_f32_e32 v214, v214
	s_waitcnt lgkmcnt(4)
	v_mfma_f32_32x32x16_bf16 v[16:31], v[244:247], v[144:147], v[16:31]
	v_exp_f32_e32 v215, v215
	v_add_f32_e32 v243, v200, v201
	v_add_f32_e32 v243, v202, v243
	v_add_f32_e32 v243, v203, v243
	v_add_f32_e32 v243, v204, v243
	s_waitcnt lgkmcnt(3)
	v_mfma_f32_32x32x16_bf16 v[112:127], v[220:223], v[148:151], v[112:127]
	v_add_f32_e32 v243, v205, v243
	v_add_f32_e32 v243, v206, v243
	v_add_f32_e32 v243, v207, v243
	v_add_f32_e32 v243, v208, v243
	v_add_f32_e32 v243, v209, v243
	s_waitcnt lgkmcnt(2)
	v_mfma_f32_32x32x16_bf16 v[80:95], v[228:231], v[148:151], v[80:95]
	v_add_f32_e32 v243, v210, v243
	v_add_f32_e32 v243, v211, v243
	v_add_f32_e32 v243, v212, v243
	v_add_f32_e32 v243, v213, v243
	v_add_f32_e32 v243, v214, v243
	s_waitcnt lgkmcnt(1)
	v_mfma_f32_32x32x16_bf16 v[48:63], v[236:239], v[148:151], v[48:63]
	v_add_f32_e32 v243, v215, v243
	v_add_f32_e32 v197, v197, v243
	v_cvt_pk_bf16_f32 v200, v200, v201
	v_cvt_pk_bf16_f32 v201, v202, v203
	v_cvt_pk_bf16_f32 v202, v204, v205
	s_waitcnt lgkmcnt(0)
	v_mfma_f32_32x32x16_bf16 v[16:31], v[248:251], v[148:151], v[16:31]
	v_cvt_pk_bf16_f32 v203, v206, v207
	v_cvt_pk_bf16_f32 v204, v208, v209
	v_cvt_pk_bf16_f32 v205, v210, v211
	v_cvt_pk_bf16_f32 v206, v212, v213
	v_cvt_pk_bf16_f32 v207, v214, v215
	ds_read_b128 v[252:255], v199 offset:4608
	ds_read_b128 v[208:211], v193
	ds_read_b128 v[212:215], v199 offset:4640
	v_mfma_f32_32x32x16_bf16 v[128:143], v[216:219], v[200:203], v[128:143]
	v_mfma_f32_32x32x16_bf16 v[96:111], v[224:227], v[200:203], v[96:111]
	v_mfma_f32_32x32x16_bf16 v[64:79], v[232:235], v[200:203], v[64:79]
	v_mfma_f32_32x32x16_bf16 v[32:47], v[244:247], v[200:203], v[32:47]
	v_mfma_f32_32x32x16_bf16 v[128:143], v[220:223], v[204:207], v[128:143]
	v_mfma_f32_32x32x16_bf16 v[96:111], v[228:231], v[204:207], v[96:111]
	v_mfma_f32_32x32x16_bf16 v[64:79], v[236:239], v[204:207], v[64:79]
	v_mfma_f32_32x32x16_bf16 v[32:47], v[248:251], v[204:207], v[32:47]
	ds_read_b128 v[236:239], v193 offset:32
	ds_read_b128 v[224:227], v199 offset:4672
	ds_read_b128 v[244:247], v193 offset:64
	ds_read_b128 v[228:231], v199 offset:4704
	ds_read_b128 v[248:251], v193 offset:96
	s_waitcnt lgkmcnt(6)
	v_mfma_f32_32x32x16_bf16 v[144:159], v[252:255], v[208:211], v[0:15]
	s_waitcnt lgkmcnt(4)
	v_mfma_f32_32x32x16_bf16 v[144:159], v[212:215], v[236:239], v[144:159]
	s_waitcnt lgkmcnt(2)
	v_mfma_f32_32x32x16_bf16 v[144:159], v[224:227], v[244:247], v[144:159]
	s_waitcnt lgkmcnt(0)
	v_mfma_f32_32x32x16_bf16 v[144:159], v[228:231], v[248:251], v[144:159]
	ds_read_b128 v[216:219], v199 offset:13824
	ds_read_b128 v[232:235], v193 offset:36864
	ds_read_b128 v[220:223], v199 offset:13856
	ds_read_b128 v[236:239], v193 offset:36896
	ds_read_b128 v[224:227], v199 offset:13888
	ds_read_b128 v[244:247], v193 offset:36928
	ds_read_b128 v[228:231], v199 offset:13920
	ds_read_b128 v[248:251], v193 offset:36960
	s_nop 3
	v_exp_f32_e32 v144, v144
	v_exp_f32_e32 v145, v145
	v_exp_f32_e32 v146, v146
	v_exp_f32_e32 v147, v147
	v_exp_f32_e32 v148, v148
	v_exp_f32_e32 v149, v149
	v_exp_f32_e32 v150, v150
	v_exp_f32_e32 v151, v151
	v_exp_f32_e32 v152, v152
	v_exp_f32_e32 v153, v153
	v_exp_f32_e32 v154, v154
	v_exp_f32_e32 v155, v155
	v_exp_f32_e32 v156, v156
	v_exp_f32_e32 v157, v157
	v_exp_f32_e32 v158, v158
	v_exp_f32_e32 v159, v159
	v_add_f32_e32 v243, v144, v145
	v_add_f32_e32 v243, v146, v243
	v_add_f32_e32 v243, v147, v243
	v_add_f32_e32 v243, v148, v243
	v_add_f32_e32 v243, v149, v243
	v_add_f32_e32 v243, v150, v243
	v_add_f32_e32 v243, v151, v243
	s_waitcnt lgkmcnt(6)
	v_mfma_f32_32x32x16_bf16 v[200:215], v[216:219], v[232:235], v[0:15]
	v_add_f32_e32 v243, v152, v243
	v_add_f32_e32 v243, v153, v243
	v_add_f32_e32 v243, v154, v243
	v_add_f32_e32 v243, v155, v243
	s_waitcnt lgkmcnt(4)
	v_mfma_f32_32x32x16_bf16 v[200:215], v[220:223], v[236:239], v[200:215]
	v_add_f32_e32 v243, v156, v243
	v_add_f32_e32 v243, v157, v243
	v_add_f32_e32 v243, v158, v243
	v_add_f32_e32 v243, v159, v243
	s_waitcnt lgkmcnt(2)
	v_mfma_f32_32x32x16_bf16 v[200:215], v[224:227], v[244:247], v[200:215]
	v_add_f32_e32 v196, v196, v243
	v_cvt_pk_bf16_f32 v144, v144, v145
	v_cvt_pk_bf16_f32 v145, v146, v147
	v_cvt_pk_bf16_f32 v146, v148, v149
	s_waitcnt lgkmcnt(0)
	v_mfma_f32_32x32x16_bf16 v[200:215], v[228:231], v[248:251], v[200:215]
	ds_read_b128 v[216:219], v198 offset:64
	ds_read_b128 v[224:227], v198 offset:4672
	ds_read_b128 v[232:235], v198 offset:9280
	ds_read_b128 v[244:247], v198 offset:13888
	ds_read_b128 v[220:223], v198 offset:96
	ds_read_b128 v[228:231], v198 offset:4704
	ds_read_b128 v[236:239], v198 offset:9312
	ds_read_b128 v[248:251], v198 offset:13920
	v_cvt_pk_bf16_f32 v147, v150, v151
	v_cvt_pk_bf16_f32 v148, v152, v153
	v_cvt_pk_bf16_f32 v149, v154, v155
	v_cvt_pk_bf16_f32 v150, v156, v157
	v_cvt_pk_bf16_f32 v151, v158, v159
	s_waitcnt lgkmcnt(7)
	v_mfma_f32_32x32x16_bf16 v[112:127], v[216:219], v[144:147], v[112:127]
	v_exp_f32_e32 v200, v200
	v_exp_f32_e32 v201, v201
	v_exp_f32_e32 v202, v202
	v_exp_f32_e32 v203, v203
	v_exp_f32_e32 v204, v204
	s_waitcnt lgkmcnt(6)
	v_mfma_f32_32x32x16_bf16 v[80:95], v[224:227], v[144:147], v[80:95]
	v_exp_f32_e32 v205, v205
	v_exp_f32_e32 v206, v206
	v_exp_f32_e32 v207, v207
	v_exp_f32_e32 v208, v208
	v_exp_f32_e32 v209, v209
	s_waitcnt lgkmcnt(5)
	v_mfma_f32_32x32x16_bf16 v[48:63], v[232:235], v[144:147], v[48:63]
	v_exp_f32_e32 v210, v210
	v_exp_f32_e32 v211, v211
	v_exp_f32_e32 v212, v212
	v_exp_f32_e32 v213, v213
	v_exp_f32_e32 v214, v214
	s_waitcnt lgkmcnt(4)
	v_mfma_f32_32x32x16_bf16 v[16:31], v[244:247], v[144:147], v[16:31]
	v_exp_f32_e32 v215, v215
	v_add_f32_e32 v243, v200, v201
	v_add_f32_e32 v243, v202, v243
	v_add_f32_e32 v243, v203, v243
	v_add_f32_e32 v243, v204, v243
	s_waitcnt lgkmcnt(3)
	v_mfma_f32_32x32x16_bf16 v[112:127], v[220:223], v[148:151], v[112:127]
	v_add_f32_e32 v243, v205, v243
	v_add_f32_e32 v243, v206, v243
	v_add_f32_e32 v243, v207, v243
	v_add_f32_e32 v243, v208, v243
	v_add_f32_e32 v243, v209, v243
	s_waitcnt lgkmcnt(2)
	v_mfma_f32_32x32x16_bf16 v[80:95], v[228:231], v[148:151], v[80:95]
	v_add_f32_e32 v243, v210, v243
	v_add_f32_e32 v243, v211, v243
	v_add_f32_e32 v243, v212, v243
	v_add_f32_e32 v243, v213, v243
	v_add_f32_e32 v243, v214, v243
	s_waitcnt lgkmcnt(1)
	v_mfma_f32_32x32x16_bf16 v[48:63], v[236:239], v[148:151], v[48:63]
	v_add_f32_e32 v243, v215, v243
	v_add_f32_e32 v197, v197, v243
	v_cvt_pk_bf16_f32 v200, v200, v201
	v_cvt_pk_bf16_f32 v201, v202, v203
	v_cvt_pk_bf16_f32 v202, v204, v205
	s_waitcnt lgkmcnt(0)
	v_mfma_f32_32x32x16_bf16 v[16:31], v[248:251], v[148:151], v[16:31]
	v_cvt_pk_bf16_f32 v203, v206, v207
	v_cvt_pk_bf16_f32 v204, v208, v209
	v_cvt_pk_bf16_f32 v205, v210, v211
	v_cvt_pk_bf16_f32 v206, v212, v213
	v_cvt_pk_bf16_f32 v207, v214, v215
	s_add_i32 s6, s42, 1
	s_waitcnt vmcnt(0)
	s_cmp_eq_u32 s33, 0
	s_cbranch_scc0 .Lqt_s0_2
	v_add_u32_e32 v252, 0x9000, v190
	ds_write_b128 v189, v[160:163] offset:36864
	ds_write2_b64 v252, v[164:165], v[166:167] offset1:2
	ds_write_b128 v189, v[168:171] offset:46080
	v_add_u32_e32 v252, 0xb000, v190
	ds_write2_b64 v252, v[172:173], v[174:175] offset0:128 offset1:130
	s_branch .Lqt_pf_2
